# N-tile relabelling re-optimised for the per-CU sum of epilogue costs (both co-resident workgroups)
# baseline (speedup 1.0000x reference)
.LBB0_219:
	s_lshr_b32 s2, s4, 2
	s_and_b32 s3, s4, 3
	s_lshl_b32 s3, s3, 3
	s_mov_b32 s6, 0x6081c0b
	s_cmp_eq_u32 s2, 1
	s_cselect_b32 s6, 0x9191601, s6
	s_cmp_eq_u32 s2, 2
	s_cselect_b32 s6, 0x1013141b, s6
	s_cmp_eq_u32 s2, 3
	s_cselect_b32 s6, 0xc0f1d, s6
	s_cmp_eq_u32 s2, 4
	s_cselect_b32 s6, 0x111a0e02, s6
	s_cmp_eq_u32 s2, 5
	s_cselect_b32 s6, 0x150d0a03, s6
	s_cmp_eq_u32 s2, 6
	s_cselect_b32 s6, 0x18050412, s6
	s_cmp_eq_u32 s2, 7
	s_cselect_b32 s6, 0x1707, s6
	s_lshr_b32 s6, s6, s3
	s_and_b32 s4, s6, 0xff
	s_lshl_b32 s5, s5, 8
	v_add_u32_e32 v2, s5, v219
	v_ashrrev_i32_e32 v3, 31, v2
	v_lshlrev_b64 v[4:5], 11, v[2:3]
	v_and_b32_e32 v6, 0xfffe7000, v4
	v_mov_b32_e32 v7, v5
	v_lshlrev_b32_e32 v0, 6, v2
	s_lshl_b32 s6, s4, 7
	v_lshl_add_u64 v[6:7], s[44:45], 0, v[6:7]
	v_and_b32_e32 v0, 64, v0
	v_lshl_add_u64 v[2:3], v[6:7], 0, v[0:1]
	v_add_u32_e32 v6, s6, v220
	v_ashrrev_i32_e32 v7, 31, v6
	v_lshlrev_b64 v[8:9], 11, v[6:7]
	v_and_b32_e32 v10, 0xffff7000, v8
	v_mov_b32_e32 v11, v9
	v_lshlrev_b32_e32 v0, 6, v6
	v_lshl_add_u64 v[10:11], s[42:43], 0, v[10:11]
	v_and_b32_e32 v0, 64, v0
	v_mov_b32_e32 v139, v1
	v_lshl_add_u64 v[6:7], v[10:11], 0, v[0:1]
	v_readfirstlane_b32 s2, v221
	v_add_u32_e32 v0, 0x400, v221
	v_lshl_add_u64 v[2:3], v[2:3], 0, v[138:139]
	s_waitcnt vmcnt(0)
	s_mov_b32 m0, s2
	s_mov_b64 s[8:9], 0x8000
	v_readfirstlane_b32 s2, v0
	global_load_lds_dwordx4 v[2:3], off
	v_lshl_add_u64 v[10:11], v[2:3], 0, s[8:9]
	s_mov_b32 m0, s2
	s_mov_b64 s[2:3], 0x10000
	v_add_u32_e32 v0, 0x800, v221
	global_load_lds_dwordx4 v[10:11], off
	v_lshl_add_u64 v[10:11], v[2:3], 0, s[2:3]
	v_readfirstlane_b32 s2, v0
	s_mov_b32 m0, s2
	s_mov_b64 s[2:3], 0x18000
	v_add_u32_e32 v0, 0xc00, v221
	global_load_lds_dwordx4 v[10:11], off
	v_lshl_add_u64 v[10:11], v[2:3], 0, s[2:3]
	v_readfirstlane_b32 s2, v0
	v_add_u32_e32 v0, 0x4000, v130
	s_mov_b32 m0, s2
	v_readfirstlane_b32 s2, v0
	v_add_u32_e32 v0, 0x4400, v130
	v_lshl_add_u64 v[6:7], v[6:7], 0, v[138:139]
	global_load_lds_dwordx4 v[10:11], off
	s_mov_b32 m0, s2
	v_readfirstlane_b32 s2, v0
	v_add_u32_e32 v0, 0x6000, v221
	global_load_lds_dwordx4 v[6:7], off
	v_lshl_add_u64 v[10:11], v[6:7], 0, s[8:9]
	s_mov_b32 m0, s2
	s_mov_b64 s[8:9], 0x80
	v_readfirstlane_b32 s2, v0
	v_add_u32_e32 v0, 0x6400, v221
	global_load_lds_dwordx4 v[10:11], off
	v_lshl_add_u64 v[10:11], v[2:3], 0, s[8:9]
	s_mov_b32 m0, s2
	s_mov_b64 s[30:31], 0x8080
	v_readfirstlane_b32 s2, v0
	global_load_lds_dwordx4 v[10:11], off
	v_lshl_add_u64 v[10:11], v[2:3], 0, s[30:31]
	s_mov_b32 m0, s2
	s_mov_b64 s[2:3], 0x10080
	v_add_u32_e32 v0, 0x6800, v221
	global_load_lds_dwordx4 v[10:11], off
	v_lshl_add_u64 v[10:11], v[2:3], 0, s[2:3]
	v_readfirstlane_b32 s2, v0
	s_mov_b32 m0, s2
	s_mov_b64 s[2:3], 0x18080
	v_add_u32_e32 v0, 0x6c00, v221
	v_lshl_add_u64 v[2:3], v[2:3], 0, s[2:3]
	v_readfirstlane_b32 s2, v0
	v_add_u32_e32 v0, 0xa000, v130
	global_load_lds_dwordx4 v[10:11], off
	s_mov_b32 m0, s2
	v_readfirstlane_b32 s2, v0
	v_add_u32_e32 v0, 0xa400, v130
	global_load_lds_dwordx4 v[2:3], off
	v_lshl_add_u64 v[2:3], v[6:7], 0, s[8:9]
	s_mov_b32 m0, s2
	v_readfirstlane_b32 s2, v0
	global_load_lds_dwordx4 v[2:3], off
	v_lshl_add_u64 v[2:3], v[6:7], 0, s[30:31]
	s_mov_b32 m0, s2
	v_and_b32_e32 v8, 0xfffff000, v8
	global_load_lds_dwordx4 v[2:3], off
	v_and_b32_e32 v4, 0xfffff000, v4
	v_mov_b32_e32 v2, 0
	v_lshl_add_u64 v[142:143], v[134:135], 0, v[8:9]
	v_lshl_add_u64 v[144:145], v[136:137], 0, v[4:5]
	s_mov_b32 s7, 0
	s_mov_b64 s[2:3], 0
	v_mov_b32_e32 v3, v2
	v_mov_b32_e32 v4, v2
	v_mov_b32_e32 v5, v2
	v_mov_b32_e32 v6, v2
	v_mov_b32_e32 v7, v2
	v_mov_b32_e32 v8, v2
	v_mov_b32_e32 v9, v2
	v_mov_b32_e32 v10, v2
	v_mov_b32_e32 v11, v2
	v_mov_b32_e32 v12, v2
	v_mov_b32_e32 v13, v2
	v_mov_b32_e32 v14, v2
	v_mov_b32_e32 v15, v2
	v_mov_b32_e32 v16, v2
	v_mov_b32_e32 v17, v2
	v_mov_b32_e32 v18, v2
	v_mov_b32_e32 v19, v2
	v_mov_b32_e32 v20, v2
	v_mov_b32_e32 v21, v2
	v_mov_b32_e32 v22, v2
	v_mov_b32_e32 v23, v2
	v_mov_b32_e32 v24, v2
	v_mov_b32_e32 v25, v2
	v_mov_b32_e32 v26, v2
	v_mov_b32_e32 v27, v2
	v_mov_b32_e32 v28, v2
	v_mov_b32_e32 v29, v2
	v_mov_b32_e32 v30, v2
	v_mov_b32_e32 v31, v2
	v_mov_b32_e32 v32, v2
	v_mov_b32_e32 v33, v2
	v_mov_b32_e32 v34, v2
	v_mov_b32_e32 v35, v2
	v_mov_b32_e32 v36, v2
	v_mov_b32_e32 v37, v2
	v_mov_b32_e32 v38, v2
	v_mov_b32_e32 v39, v2
	v_mov_b32_e32 v40, v2
	v_mov_b32_e32 v41, v2
	v_mov_b32_e32 v42, v2
	v_mov_b32_e32 v43, v2
	v_mov_b32_e32 v44, v2
	v_mov_b32_e32 v45, v2
	v_mov_b32_e32 v46, v2
	v_mov_b32_e32 v47, v2
	v_mov_b32_e32 v48, v2
	v_mov_b32_e32 v49, v2
	s_waitcnt vmcnt(0)
	v_mov_b32_e32 v50, v2
	v_mov_b32_e32 v51, v2
	v_mov_b32_e32 v52, v2
	v_mov_b32_e32 v53, v2
	v_mov_b32_e32 v54, v2
	v_mov_b32_e32 v55, v2
	v_mov_b32_e32 v56, v2
	v_mov_b32_e32 v57, v2
	v_mov_b32_e32 v58, v2
	v_mov_b32_e32 v59, v2
	v_mov_b32_e32 v60, v2
	v_mov_b32_e32 v61, v2
	v_mov_b32_e32 v62, v2
	v_mov_b32_e32 v63, v2
	v_mov_b32_e32 v64, v2
	v_mov_b32_e32 v65, v2
	v_mov_b32_e32 v66, v2
	v_mov_b32_e32 v67, v2
	v_mov_b32_e32 v68, v2
	v_mov_b32_e32 v69, v2
	v_mov_b32_e32 v70, v2
	v_mov_b32_e32 v71, v2
	v_mov_b32_e32 v72, v2
	v_mov_b32_e32 v73, v2
	v_mov_b32_e32 v74, v2
	v_mov_b32_e32 v75, v2
	v_mov_b32_e32 v76, v2
	v_mov_b32_e32 v77, v2
	v_mov_b32_e32 v78, v2
	v_mov_b32_e32 v79, v2
	v_mov_b32_e32 v80, v2
	v_mov_b32_e32 v81, v2
	v_mov_b32_e32 v82, v2
	v_mov_b32_e32 v83, v2
	v_mov_b32_e32 v84, v2
	v_mov_b32_e32 v85, v2
	v_mov_b32_e32 v86, v2
	v_mov_b32_e32 v87, v2
	v_mov_b32_e32 v88, v2
	v_mov_b32_e32 v89, v2
	v_mov_b32_e32 v90, v2
	v_mov_b32_e32 v91, v2
	v_mov_b32_e32 v92, v2
	v_mov_b32_e32 v93, v2
	v_mov_b32_e32 v94, v2
	v_mov_b32_e32 v95, v2
	v_mov_b32_e32 v96, v2
	v_mov_b32_e32 v97, v2
	v_mov_b32_e32 v98, v2
	v_mov_b32_e32 v99, v2
	v_mov_b32_e32 v100, v2
	v_mov_b32_e32 v101, v2
	v_mov_b32_e32 v102, v2
	v_mov_b32_e32 v103, v2
	v_mov_b32_e32 v104, v2
	v_mov_b32_e32 v105, v2
	v_mov_b32_e32 v106, v2
	v_mov_b32_e32 v107, v2
	v_mov_b32_e32 v108, v2
	v_mov_b32_e32 v109, v2
	v_mov_b32_e32 v110, v2
	v_mov_b32_e32 v111, v2
	v_mov_b32_e32 v112, v2
	v_mov_b32_e32 v113, v2
	v_mov_b32_e32 v114, v2
	v_mov_b32_e32 v115, v2
	v_mov_b32_e32 v116, v2
	v_mov_b32_e32 v117, v2
	v_mov_b32_e32 v118, v2
	v_mov_b32_e32 v119, v2
	v_mov_b32_e32 v120, v2
	v_mov_b32_e32 v121, v2
	v_mov_b32_e32 v122, v2
	v_mov_b32_e32 v123, v2
	v_mov_b32_e32 v124, v2
	v_mov_b32_e32 v125, v2
	v_mov_b32_e32 v126, v2
	v_mov_b32_e32 v127, v2
	v_mov_b32_e32 v128, v2
	v_mov_b32_e32 v129, v2
